# grid barriers: the globally last XCD leader releases all eight XCD generation words directly; other leaders wait like followers (one hop less)
# baseline (speedup 1.0000x reference)
.LBB0_127:
	s_waitcnt vmcnt(0)
	s_barrier
	s_mov_b64 s[2:3], exec
	v_readlane_b32 s4, v248, 7
	v_readlane_b32 s5, v248, 8
	s_and_b64 s[4:5], s[2:3], s[4:5]
	s_mov_b64 exec, s[4:5]
	s_cbranch_execz .LBB0_179
	v_readlane_b32 s4, v248, 4
	v_readlane_b32 s5, v248, 5
	v_readlane_b32 s8, v248, 6
	v_readlane_b32 s9, v249, 14
	v_readlane_b32 s10, v249, 15
	v_mov_b32_e32 v1, 1
	v_mov_b32_e32 v3, 0x3400
	s_nop 1
	s_lshl_b32 s8, s8, 8
	s_mul_i32 s9, s9, 2
	s_mul_i32 s10, s10, 2
	v_mov_b32_e32 v0, s8
	v_add_u32_e32 v2, 0x1000, v0
	v_add_u32_e32 v4, 0x2000, v0
	s_nop 1
	global_atomic_add v5, v2, v1, s[4:5] offset:1024 sc0
	s_waitcnt vmcnt(0)
	v_readfirstlane_b32 s11, v5
	s_nop 1
	s_add_u32 s11, s11, 1
	s_cmp_eq_u32 s11, s9
	s_cbranch_scc0 .Lhb1_follower
	buffer_wbl2 sc1
	s_waitcnt vmcnt(0)
	buffer_inv sc1
	global_atomic_add v5, v3, v1, s[4:5] sc0
	s_waitcnt vmcnt(0)
	v_readfirstlane_b32 s11, v5
	s_nop 1
	s_add_u32 s11, s11, 1
	s_cmp_ge_u32 s11, s10
	s_cbranch_scc0 .Lhb1_fwait
	v_mov_b32_e32 v5, 0x2400
	global_atomic_add v5, v1, s[4:5]
	global_atomic_add v5, v1, s[4:5] offset:256
	global_atomic_add v5, v1, s[4:5] offset:512
	global_atomic_add v5, v1, s[4:5] offset:768
	global_atomic_add v5, v1, s[4:5] offset:1024
	global_atomic_add v5, v1, s[4:5] offset:1280
	global_atomic_add v5, v1, s[4:5] offset:1536
	global_atomic_add v5, v1, s[4:5] offset:1792
	s_branch .Lhb1_done

.Lhb1_fwait:
	s_movk_i32 s12, 0x1000

.LBB0_309:
	s_waitcnt vmcnt(0)
	s_barrier
	s_mov_b64 s[2:3], exec
	v_readlane_b32 s4, v248, 7
	v_readlane_b32 s5, v248, 8
	s_and_b64 s[4:5], s[2:3], s[4:5]
	s_mov_b64 exec, s[4:5]
	s_cbranch_execz .LBB0_361
	v_readlane_b32 s4, v248, 4
	v_readlane_b32 s5, v248, 5
	v_readlane_b32 s8, v248, 6
	v_readlane_b32 s9, v249, 14
	v_readlane_b32 s10, v249, 15
	v_mov_b32_e32 v1, 1
	v_mov_b32_e32 v3, 0x3400
	s_nop 1
	s_lshl_b32 s8, s8, 8
	s_mul_i32 s9, s9, 3
	s_mul_i32 s10, s10, 3
	v_mov_b32_e32 v0, s8
	v_add_u32_e32 v2, 0x1000, v0
	v_add_u32_e32 v4, 0x2000, v0
	s_nop 1
	global_atomic_add v5, v2, v1, s[4:5] offset:1024 sc0
	s_waitcnt vmcnt(0)
	v_readfirstlane_b32 s11, v5
	s_nop 1
	s_add_u32 s11, s11, 1
	s_cmp_eq_u32 s11, s9
	s_cbranch_scc0 .Lhb2_follower
	buffer_wbl2 sc1
	s_waitcnt vmcnt(0)
	buffer_inv sc1
	global_atomic_add v5, v3, v1, s[4:5] sc0
	s_waitcnt vmcnt(0)
	v_readfirstlane_b32 s11, v5
	s_nop 1
	s_add_u32 s11, s11, 1
	s_cmp_ge_u32 s11, s10
	s_cbranch_scc0 .Lhb2_fwait
	v_mov_b32_e32 v5, 0x2400
	global_atomic_add v5, v1, s[4:5]
	global_atomic_add v5, v1, s[4:5] offset:256
	global_atomic_add v5, v1, s[4:5] offset:512
	global_atomic_add v5, v1, s[4:5] offset:768
	global_atomic_add v5, v1, s[4:5] offset:1024
	global_atomic_add v5, v1, s[4:5] offset:1280
	global_atomic_add v5, v1, s[4:5] offset:1536
	global_atomic_add v5, v1, s[4:5] offset:1792
	s_branch .Lhb2_done

.LBB0_616:
	s_waitcnt vmcnt(0)
	s_barrier
	s_mov_b64 s[2:3], exec
	v_readlane_b32 s4, v248, 7
	v_readlane_b32 s5, v248, 8
	s_and_b64 s[4:5], s[2:3], s[4:5]
	s_mov_b64 exec, s[4:5]
	s_cbranch_execz .LBB0_668
	v_readlane_b32 s4, v248, 4
	v_readlane_b32 s5, v248, 5
	v_readlane_b32 s8, v248, 6
	v_readlane_b32 s9, v249, 14
	v_readlane_b32 s10, v249, 15
	v_mov_b32_e32 v1, 1
	v_mov_b32_e32 v3, 0x3400
	s_nop 1
	s_lshl_b32 s8, s8, 8
	s_mul_i32 s9, s9, 4
	s_mul_i32 s10, s10, 4
	v_mov_b32_e32 v0, s8
	v_add_u32_e32 v2, 0x1000, v0
	v_add_u32_e32 v4, 0x2000, v0
	s_nop 1
	global_atomic_add v5, v2, v1, s[4:5] offset:1024 sc0
	s_waitcnt vmcnt(0)
	v_readfirstlane_b32 s11, v5
	s_nop 1
	s_add_u32 s11, s11, 1
	s_cmp_eq_u32 s11, s9
	s_cbranch_scc0 .Lhb3_follower
	buffer_wbl2 sc1
	s_waitcnt vmcnt(0)
	buffer_inv sc1
	global_atomic_add v5, v3, v1, s[4:5] sc0
	s_waitcnt vmcnt(0)
	v_readfirstlane_b32 s11, v5
	s_nop 1
	s_add_u32 s11, s11, 1
	s_cmp_ge_u32 s11, s10
	s_cbranch_scc0 .Lhb3_fwait
	v_mov_b32_e32 v5, 0x2400
	global_atomic_add v5, v1, s[4:5]
	global_atomic_add v5, v1, s[4:5] offset:256
	global_atomic_add v5, v1, s[4:5] offset:512
	global_atomic_add v5, v1, s[4:5] offset:768
	global_atomic_add v5, v1, s[4:5] offset:1024
	global_atomic_add v5, v1, s[4:5] offset:1280
	global_atomic_add v5, v1, s[4:5] offset:1536
	global_atomic_add v5, v1, s[4:5] offset:1792
	s_branch .Lhb3_done

.LBB0_686:
	s_waitcnt vmcnt(0)
	s_waitcnt vmcnt(63) expcnt(7) lgkmcnt(15)
	s_barrier
	s_mov_b64 s[2:3], exec
	v_readlane_b32 s4, v248, 7
	v_readlane_b32 s5, v248, 8
	s_and_b64 s[4:5], s[2:3], s[4:5]
	s_mov_b64 exec, s[4:5]
	s_cbranch_execz .LBB0_738
	v_readlane_b32 s4, v248, 4
	v_readlane_b32 s5, v248, 5
	v_readlane_b32 s8, v248, 6
	v_readlane_b32 s9, v249, 14
	v_readlane_b32 s10, v249, 15
	v_mov_b32_e32 v1, 1
	v_mov_b32_e32 v3, 0x3400
	s_nop 1
	s_lshl_b32 s8, s8, 8
	s_mul_i32 s9, s9, 5
	s_mul_i32 s10, s10, 5
	v_mov_b32_e32 v0, s8
	v_add_u32_e32 v2, 0x1000, v0
	v_add_u32_e32 v4, 0x2000, v0
	s_nop 1
	global_atomic_add v5, v2, v1, s[4:5] offset:1024 sc0
	s_waitcnt vmcnt(0)
	v_readfirstlane_b32 s11, v5
	s_nop 1
	s_add_u32 s11, s11, 1
	s_cmp_eq_u32 s11, s9
	s_cbranch_scc0 .Lhb4_follower
	buffer_wbl2 sc1
	s_waitcnt vmcnt(0)
	buffer_inv sc1
	global_atomic_add v5, v3, v1, s[4:5] sc0
	s_waitcnt vmcnt(0)
	v_readfirstlane_b32 s11, v5
	s_nop 1
	s_add_u32 s11, s11, 1
	s_cmp_ge_u32 s11, s10
	s_cbranch_scc0 .Lhb4_fwait
	v_mov_b32_e32 v5, 0x2400
	global_atomic_add v5, v1, s[4:5]
	global_atomic_add v5, v1, s[4:5] offset:256
	global_atomic_add v5, v1, s[4:5] offset:512
	global_atomic_add v5, v1, s[4:5] offset:768
	global_atomic_add v5, v1, s[4:5] offset:1024
	global_atomic_add v5, v1, s[4:5] offset:1280
	global_atomic_add v5, v1, s[4:5] offset:1536
	global_atomic_add v5, v1, s[4:5] offset:1792
	s_branch .Lhb4_done

.LBB0_819:
	s_waitcnt vmcnt(0)
	s_barrier
	s_mov_b64 s[2:3], exec
	v_readlane_b32 s4, v248, 7
	v_readlane_b32 s5, v248, 8
	s_and_b64 s[4:5], s[2:3], s[4:5]
	s_mov_b64 exec, s[4:5]
	s_cbranch_execz .LBB0_871
	v_readlane_b32 s4, v248, 4
	v_readlane_b32 s5, v248, 5
	v_readlane_b32 s8, v248, 6
	v_readlane_b32 s9, v249, 14
	v_readlane_b32 s10, v249, 15
	v_mov_b32_e32 v1, 1
	v_mov_b32_e32 v3, 0x3400
	s_nop 1
	s_lshl_b32 s8, s8, 8
	s_mul_i32 s9, s9, 6
	s_mul_i32 s10, s10, 6
	v_mov_b32_e32 v0, s8
	v_add_u32_e32 v2, 0x1000, v0
	v_add_u32_e32 v4, 0x2000, v0
	s_nop 1
	global_atomic_add v5, v2, v1, s[4:5] offset:1024 sc0
	s_waitcnt vmcnt(0)
	v_readfirstlane_b32 s11, v5
	s_nop 1
	s_add_u32 s11, s11, 1
	s_cmp_eq_u32 s11, s9
	s_cbranch_scc0 .Lhb5_follower
	buffer_wbl2 sc1
	s_waitcnt vmcnt(0)
	buffer_inv sc1
	global_atomic_add v5, v3, v1, s[4:5] sc0
	s_waitcnt vmcnt(0)
	v_readfirstlane_b32 s11, v5
	s_nop 1
	s_add_u32 s11, s11, 1
	s_cmp_ge_u32 s11, s10
	s_cbranch_scc0 .Lhb5_fwait
	v_mov_b32_e32 v5, 0x2400
	global_atomic_add v5, v1, s[4:5]
	global_atomic_add v5, v1, s[4:5] offset:256
	global_atomic_add v5, v1, s[4:5] offset:512
	global_atomic_add v5, v1, s[4:5] offset:768
	global_atomic_add v5, v1, s[4:5] offset:1024
	global_atomic_add v5, v1, s[4:5] offset:1280
	global_atomic_add v5, v1, s[4:5] offset:1536
	global_atomic_add v5, v1, s[4:5] offset:1792
	s_branch .Lhb5_done

.LBB0_904:
	s_waitcnt vmcnt(0)
	s_barrier
	s_mov_b64 s[2:3], exec
	v_readlane_b32 s4, v248, 7
	v_readlane_b32 s5, v248, 8
	s_and_b64 s[4:5], s[2:3], s[4:5]
	s_mov_b64 exec, s[4:5]
	s_cbranch_execz .LBB0_956
	v_readlane_b32 s4, v248, 4
	v_readlane_b32 s5, v248, 5
	v_readlane_b32 s8, v248, 6
	v_readlane_b32 s9, v249, 14
	v_readlane_b32 s10, v249, 15
	v_mov_b32_e32 v1, 1
	v_mov_b32_e32 v3, 0x3400
	s_nop 1
	s_lshl_b32 s8, s8, 8
	s_mul_i32 s9, s9, 7
	s_mul_i32 s10, s10, 7
	v_mov_b32_e32 v0, s8
	v_add_u32_e32 v2, 0x1000, v0
	v_add_u32_e32 v4, 0x2000, v0
	s_nop 1
	global_atomic_add v5, v2, v1, s[4:5] offset:1024 sc0
	s_waitcnt vmcnt(0)
	v_readfirstlane_b32 s11, v5
	s_nop 1
	s_add_u32 s11, s11, 1
	s_cmp_eq_u32 s11, s9
	s_cbranch_scc0 .Lhb6_follower
	buffer_wbl2 sc1
	s_waitcnt vmcnt(0)
	buffer_inv sc1
	global_atomic_add v5, v3, v1, s[4:5] sc0
	s_waitcnt vmcnt(0)
	v_readfirstlane_b32 s11, v5
	s_nop 1
	s_add_u32 s11, s11, 1
	s_cmp_ge_u32 s11, s10
	s_cbranch_scc0 .Lhb6_fwait
	v_mov_b32_e32 v5, 0x2400
	global_atomic_add v5, v1, s[4:5]
	global_atomic_add v5, v1, s[4:5] offset:256
	global_atomic_add v5, v1, s[4:5] offset:512
	global_atomic_add v5, v1, s[4:5] offset:768
	global_atomic_add v5, v1, s[4:5] offset:1024
	global_atomic_add v5, v1, s[4:5] offset:1280
	global_atomic_add v5, v1, s[4:5] offset:1536
	global_atomic_add v5, v1, s[4:5] offset:1792
	s_branch .Lhb6_done

.LBB0_1019:
	s_waitcnt vmcnt(0)
	s_barrier
	s_mov_b64 s[2:3], exec
	v_readlane_b32 s4, v248, 7
	v_readlane_b32 s5, v248, 8
	s_and_b64 s[4:5], s[2:3], s[4:5]
	s_mov_b64 exec, s[4:5]
	s_cbranch_execz .LBB0_1071
	v_readlane_b32 s4, v248, 4
	v_readlane_b32 s5, v248, 5
	v_readlane_b32 s8, v248, 6
	v_readlane_b32 s9, v249, 14
	v_readlane_b32 s10, v249, 15
	v_mov_b32_e32 v1, 1
	v_mov_b32_e32 v3, 0x3400
	s_nop 1
	s_lshl_b32 s8, s8, 8
	s_mul_i32 s9, s9, 8
	s_mul_i32 s10, s10, 8
	v_mov_b32_e32 v0, s8
	v_add_u32_e32 v2, 0x1000, v0
	v_add_u32_e32 v4, 0x2000, v0
	s_nop 1
	global_atomic_add v5, v2, v1, s[4:5] offset:1024 sc0
	s_waitcnt vmcnt(0)
	v_readfirstlane_b32 s11, v5
	s_nop 1
	s_add_u32 s11, s11, 1
	s_cmp_eq_u32 s11, s9
	s_cbranch_scc0 .Lhb7_follower
	buffer_wbl2 sc1
	s_waitcnt vmcnt(0)
	buffer_inv sc1
	global_atomic_add v5, v3, v1, s[4:5] sc0
	s_waitcnt vmcnt(0)
	v_readfirstlane_b32 s11, v5
	s_nop 1
	s_add_u32 s11, s11, 1
	s_cmp_ge_u32 s11, s10
	s_cbranch_scc0 .Lhb7_fwait
	v_mov_b32_e32 v5, 0x2400
	global_atomic_add v5, v1, s[4:5]
	global_atomic_add v5, v1, s[4:5] offset:256
	global_atomic_add v5, v1, s[4:5] offset:512
	global_atomic_add v5, v1, s[4:5] offset:768
	global_atomic_add v5, v1, s[4:5] offset:1024
	global_atomic_add v5, v1, s[4:5] offset:1280
	global_atomic_add v5, v1, s[4:5] offset:1536
	global_atomic_add v5, v1, s[4:5] offset:1792
	s_branch .Lhb7_done

.LBB0_1079:
	s_waitcnt vmcnt(0)
	s_barrier
	s_mov_b64 s[2:3], exec
	v_readlane_b32 s4, v248, 7
	v_readlane_b32 s5, v248, 8
	s_and_b64 s[4:5], s[2:3], s[4:5]
	s_mov_b64 exec, s[4:5]
	s_cbranch_execz .LBB0_1131
	v_readlane_b32 s4, v248, 4
	v_readlane_b32 s5, v248, 5
	v_readlane_b32 s8, v248, 6
	v_readlane_b32 s9, v249, 14
	v_readlane_b32 s10, v249, 15
	v_mov_b32_e32 v1, 1
	v_mov_b32_e32 v3, 0x3400
	s_nop 1
	s_lshl_b32 s8, s8, 8
	s_mul_i32 s9, s9, 9
	s_mul_i32 s10, s10, 9
	v_mov_b32_e32 v0, s8
	v_add_u32_e32 v2, 0x1000, v0
	v_add_u32_e32 v4, 0x2000, v0
	s_nop 1
	global_atomic_add v5, v2, v1, s[4:5] offset:1024 sc0
	s_waitcnt vmcnt(0)
	v_readfirstlane_b32 s11, v5
	s_nop 1
	s_add_u32 s11, s11, 1
	s_cmp_eq_u32 s11, s9
	s_cbranch_scc0 .Lhb8_follower
	buffer_wbl2 sc1
	s_waitcnt vmcnt(0)
	buffer_inv sc1
	global_atomic_add v5, v3, v1, s[4:5] sc0
	s_waitcnt vmcnt(0)
	v_readfirstlane_b32 s11, v5
	s_nop 1
	s_add_u32 s11, s11, 1
	s_cmp_ge_u32 s11, s10
	s_cbranch_scc0 .Lhb8_fwait
	v_mov_b32_e32 v5, 0x2400
	global_atomic_add v5, v1, s[4:5]
	global_atomic_add v5, v1, s[4:5] offset:256
	global_atomic_add v5, v1, s[4:5] offset:512
	global_atomic_add v5, v1, s[4:5] offset:768
	global_atomic_add v5, v1, s[4:5] offset:1024
	global_atomic_add v5, v1, s[4:5] offset:1280
	global_atomic_add v5, v1, s[4:5] offset:1536
	global_atomic_add v5, v1, s[4:5] offset:1792
	s_branch .Lhb8_done

.LBB0_1214:
	s_waitcnt vmcnt(0)
	s_barrier
	s_mov_b64 s[2:3], exec
	v_readlane_b32 s4, v248, 7
	v_readlane_b32 s5, v248, 8
	s_and_b64 s[4:5], s[2:3], s[4:5]
	s_mov_b64 exec, s[4:5]
	s_cbranch_execz .LBB0_1266
	v_readlane_b32 s4, v248, 4
	v_readlane_b32 s5, v248, 5
	v_readlane_b32 s8, v248, 6
	v_readlane_b32 s9, v249, 14
	v_readlane_b32 s10, v249, 15
	v_mov_b32_e32 v1, 1
	v_mov_b32_e32 v3, 0x3400
	s_nop 1
	s_lshl_b32 s8, s8, 8
	s_mul_i32 s9, s9, 10
	s_mul_i32 s10, s10, 10
	v_mov_b32_e32 v0, s8
	v_add_u32_e32 v2, 0x1000, v0
	v_add_u32_e32 v4, 0x2000, v0
	s_nop 1
	global_atomic_add v5, v2, v1, s[4:5] offset:1024 sc0
	s_waitcnt vmcnt(0)
	v_readfirstlane_b32 s11, v5
	s_nop 1
	s_add_u32 s11, s11, 1
	s_cmp_eq_u32 s11, s9
	s_cbranch_scc0 .Lhb9_follower
	buffer_wbl2 sc1
	s_waitcnt vmcnt(0)
	buffer_inv sc1
	global_atomic_add v5, v3, v1, s[4:5] sc0
	s_waitcnt vmcnt(0)
	v_readfirstlane_b32 s11, v5
	s_nop 1
	s_add_u32 s11, s11, 1
	s_cmp_ge_u32 s11, s10
	s_cbranch_scc0 .Lhb9_fwait
	v_mov_b32_e32 v5, 0x2400
	global_atomic_add v5, v1, s[4:5]
	global_atomic_add v5, v1, s[4:5] offset:256
	global_atomic_add v5, v1, s[4:5] offset:512
	global_atomic_add v5, v1, s[4:5] offset:768
	global_atomic_add v5, v1, s[4:5] offset:1024
	global_atomic_add v5, v1, s[4:5] offset:1280
	global_atomic_add v5, v1, s[4:5] offset:1536
	global_atomic_add v5, v1, s[4:5] offset:1792
	s_branch .Lhb9_done
